# safe subset: attention far-tile constant-bias path, dead per-tile save/restore movs removed, canonicalizing v_max dropped in relu2 epilogues
# speedup vs baseline: 1.0052x; 1.0052x over previous
; __device__ __forceinline__ float bf2f(bf16_t b) { return __uint_as_float(((unsigned)b) << 16); }
; template <int MODE>
; __device__ __forceinline__ void scan_item(const DArgs& a, LAS float* W  , int row0, int nsteps, int h, int lane, bool first_is_start, const float* shift_prev  ,
;                                           const float* S_init  , float* S_final  , float* Uout, float* Pout) {
;     ...
;     auto prep = [&](const ScanRaw& rw) -> Prep {
;         Prep o; const float zr = bf2f(rw.zr), zk = bf2f(rw.zk), zv = bf2f(rw.zv);
;         const float r = zr + (zr_p - zr) * k.mu_r, kx = zk + (zk_p - zk) * k.mu_k; o.v = zv + (zv_p - zv) * k.mu_v;
;         zr_p = zr; zk_p = zk; zv_p = zv;
;         o.dec = __expf(-0.60653066f * sigmoidf_(k.w0 + rw.lw));
;         const float ai = sigmoidf_(k.a0 + rw.la);
;         const float kkr = kx * k.kkc, ssq = wave_sum(kkr * kkr), kk = kkr * rsqrtf(fmaxf(ssq, 1e-24f));
;         o.kmod = kx * (1.f + (ai - 1.f) * k.kac); o.an = -kk; o.bn = kk * ai; o.r = r; o.lg = rw.lg; o.bin = r * o.kmod * k.rk; return o; };
;     auto post = [&](float y, float bin, float v, float lg, int row, bool doit) {
;         const float mean = wave_sum(y) * (1.f / 64.f), dy = y - mean, var = wave_sum(dy * dy) * (1.f / 64.f);
;         const float yn = dy * rsqrtf(var + 64e-5f) * k.lnw + k.lnb;
;         const float bonus = wave_sum(bin) * v;
;         if (doit) mix[(size_t)row * D + 1024 + c] = f2bf((yn + bonus) * lg); };
;     ScanRaw raw1 = scan_load<MODE == 1>(P, L, row0 + (nsteps > 1 ? 1 : 0), c);
;     Prep pv = prep(scan_load<MODE == 1>(P, L, row0, c));
;     float yp = 0.f, binp = 0.f, vp = 0.f, lgp = 0.f;
;     for (int t = 0; t < nsteps; ++t) {
;         const int row = row0 + t;
;         const ScanRaw raw2 = scan_load<MODE == 1>(P, L, row0 + (t + 2 < nsteps ? t + 2 : nsteps - 1), c);
;         W[lane] = pv.an; W[64 + lane] = pv.dec; W[128 + lane] = pv.bn; if constexpr (MODE != 2) { W[192 + lane] = pv.kmod; W[320 + lane] = pv.v; } if constexpr (MODE == 1) W[256 + lane] = pv.r;
;         const Prep pn = prep(raw1);
;         constexpr int NS = 2, PW = 8 / NS;
;         float sa[4];
; #pragma unroll
;         for (int q = 0; q < 4; ++q) sa[q] = 0.f;
; #pragma unroll
;         for (int hf = 0; hf < NS; ++hf) {
;             f32x2 av[PW];
; #pragma unroll
.LBB0_574:
	s_min_u32 s1, s0, 0x7d
	v_add_u32_e32 v110, s1, v179
	v_mad_i64_i32 v[100:101], s[16:17], v110, s24, v[94:95]
	v_add_co_u32_e32 v100, vcc, s22, v100
	s_add_i32 s0, s0, 1
	s_nop 0
	v_addc_co_u32_e32 v101, vcc, 0, v101, vcc
	global_load_ushort v188, v[100:101], off
	global_load_ushort v189, v[100:101], off offset:2048
	v_mad_i64_i32 v[100:101], s[16:17], v110, s25, v[96:97]
	global_load_dword v186, v[100:101], off
	v_add_co_u32_e32 v100, vcc, s22, v100
	s_cmpk_lg_i32 s0, 0x80
	s_nop 0
	v_addc_co_u32_e32 v101, vcc, 0, v101, vcc
	global_load_dword v187, v[100:101], off
	ds_write2st64_b32 v176, v184, v185 offset0:32 offset1:33
	ds_write2st64_b32 v176, v99, v98 offset0:34 offset1:35
	ds_write_b32 v176, v73 offset:9472
	s_waitcnt vmcnt(5)
	v_add_f32_e32 v73, v91, v108
	v_mul_f32_e32 v73, 0xbfb8aa3b, v73
	v_exp_f32_e32 v73, v73
	v_and_b32_e32 v101, 0xffff0000, v104
	v_lshlrev_b32_e32 v100, 16, v104
	v_pk_add_f32 v[190:191], v[102:103], v[100:101] neg_lo:[0,1] neg_hi:[0,1]
	v_add_f32_e32 v73, 1.0, v73
	v_rcp_f32_e32 v73, v73
	v_mov_b32_e32 v98, v101
	v_fmac_f32_e32 v98, v81, v191
	v_mov_b32_e32 v103, 0
	v_mul_f32_e32 v73, 0xbf1b4598, v73
	v_mul_f32_e32 v104, 0x3fb8aa3b, v73
	s_waitcnt vmcnt(4)
	v_add_f32_e32 v73, v181, v106
	v_mul_f32_e32 v73, 0xbfb8aa3b, v73
	v_exp_f32_e32 v73, v73
	v_exp_f32_e32 v185, v104
	v_add_f32_e32 v73, 1.0, v73
	v_rcp_f32_e32 v99, v73
	v_mul_f32_e32 v73, v182, v98
	v_mul_f32_e32 v102, v73, v73
	s_nop 1
	v_mov_b32_dpp v103, v102 quad_perm:[1,0,3,2] row_mask:0xf bank_mask:0xf
	v_fmac_f32_e32 v103, v73, v73
	s_nop 1
	v_add_f32_dpp v102, v103, v103 quad_perm:[2,3,0,1] row_mask:0xf bank_mask:0xf bound_ctrl:1
	s_nop 1
	v_add_f32_dpp v102, v102, v102 row_half_mirror row_mask:0xf bank_mask:0xf bound_ctrl:1
	s_nop 1
	v_add_f32_dpp v102, v102, v102 row_mirror row_mask:0xf bank_mask:0xf bound_ctrl:1
	s_nop 0
	v_readlane_b32 s1, v102, 16
	v_readlane_b32 s18, v102, 48
	v_readlane_b32 s16, v102, 0
	v_readlane_b32 s17, v102, 32
	v_mov_b32_e32 v102, s1
	v_mov_b32_e32 v103, s18
	v_pk_add_f32 v[102:103], s[16:17], v[102:103]
	s_nop 0
	v_add_f32_e32 v102, v102, v103
	v_max_f32_e32 v102, 0x179abe15, v102
	v_rsq_f32_e32 v103, v102
	v_add_f32_e32 v102, -1.0, v99
	v_fma_f32 v102, v183, v102, 1.0
	v_mul_f32_e64 v184, v73, -v103
	v_mov_b32_e32 v73, v100
	v_fmac_f32_e32 v73, v89, v190
	ds_read_b128 v[190:193], v177 offset:8192
	ds_read_b128 v[194:197], v177 offset:8208
	ds_read_b128 v[198:201], v177 offset:8224
	ds_read_b128 v[202:205], v177 offset:8240
	v_xor_b32_e32 v103, 0x80000000, v184
	s_waitcnt lgkmcnt(3)
	v_pk_mul_f32 v[206:207], v[70:71], v[192:193]
	v_pk_mul_f32 v[208:209], v[54:55], v[192:193]
	v_pk_mul_f32 v[210:211], v[30:31], v[192:193]
	v_pk_mul_f32 v[192:193], v[14:15], v[192:193]
	v_pk_fma_f32 v[206:207], v[68:69], v[190:191], v[206:207]
	v_pk_fma_f32 v[208:209], v[52:53], v[190:191], v[208:209]
	v_pk_fma_f32 v[210:211], v[28:29], v[190:191], v[210:211]
	v_pk_fma_f32 v[190:191], v[12:13], v[190:191], v[192:193]
	s_waitcnt lgkmcnt(1)
	v_pk_mul_f32 v[192:193], v[62:63], v[200:201]
	v_pk_fma_f32 v[206:207], v[64:65], v[194:195], v[206:207]
	v_pk_fma_f32 v[192:193], v[60:61], v[198:199], v[192:193]
	v_pk_fma_f32 v[206:207], v[66:67], v[196:197], v[206:207]
	s_waitcnt lgkmcnt(0)
	v_pk_fma_f32 v[192:193], v[56:57], v[202:203], v[192:193]
	v_pk_fma_f32 v[208:209], v[48:49], v[194:195], v[208:209]
	v_pk_fma_f32 v[192:193], v[58:59], v[204:205], v[192:193]
	v_pk_fma_f32 v[210:211], v[24:25], v[194:195], v[210:211]
	v_pk_fma_f32 v[190:191], v[8:9], v[194:195], v[190:191]
	v_mov_b32_e32 v194, v206
	v_mov_b32_e32 v195, v192
	v_mov_b32_e32 v192, v207
	v_pk_add_f32 v[192:193], v[194:195], v[192:193]
	v_pk_fma_f32 v[208:209], v[50:51], v[196:197], v[208:209]
	v_add_f32_e32 v106, 0, v192
	v_add_f32_e32 v106, v106, v193
	v_pk_mul_f32 v[192:193], v[46:47], v[200:201]
	v_mov_b32_e32 v194, v208
	v_pk_fma_f32 v[192:193], v[44:45], v[198:199], v[192:193]
	v_pk_fma_f32 v[210:211], v[26:27], v[196:197], v[210:211]
	v_pk_fma_f32 v[192:193], v[40:41], v[202:203], v[192:193]
	v_pk_fma_f32 v[190:191], v[10:11], v[196:197], v[190:191]
	v_pk_fma_f32 v[192:193], v[42:43], v[204:205], v[192:193]
	v_mov_b32_e32 v104, v106
	v_mov_b32_e32 v195, v192
	v_mov_b32_e32 v192, v209
	v_pk_add_f32 v[192:193], v[194:195], v[192:193]
	v_mov_b32_e32 v194, v210
	v_add_f32_e32 v108, 0, v192
	v_add_f32_e32 v108, v108, v193
	v_pk_mul_f32 v[192:193], v[22:23], v[200:201]
	v_permlane16_swap_b32_e32 v106, v104
	v_pk_fma_f32 v[192:193], v[20:21], v[198:199], v[192:193]
	v_add_f32_e32 v104, v106, v104
	v_pk_fma_f32 v[192:193], v[16:17], v[202:203], v[192:193]
	v_mov_b32_e32 v106, v104
	v_pk_fma_f32 v[192:193], v[18:19], v[204:205], v[192:193]
	s_nop 0
	v_permlane32_swap_b32_e32 v104, v106
	v_mov_b32_e32 v195, v192
	v_mov_b32_e32 v192, v211
	v_pk_add_f32 v[192:193], v[194:195], v[192:193]
	v_mov_b32_e32 v194, v190
	v_add_f32_e32 v110, 0, v192
	v_add_f32_e32 v196, v110, v193
	v_pk_mul_f32 v[192:193], v[38:39], v[200:201]
	v_pk_mul_f32 v[98:99], v[98:99], v[102:103]
	v_pk_fma_f32 v[192:193], v[36:37], v[198:199], v[192:193]
	v_mov_b64_e32 v[102:103], v[100:101]
	v_pk_fma_f32 v[192:193], v[32:33], v[202:203], v[192:193]
	s_nop 0
	v_pk_fma_f32 v[192:193], v[34:35], v[204:205], v[192:193]
	s_nop 0
	v_mov_b32_e32 v195, v192
	v_mov_b32_e32 v192, v191
	v_pk_add_f32 v[190:191], v[194:195], v[192:193]
	s_nop 0
	v_add_f32_e32 v110, 0, v190
	v_add_f32_e32 v190, v110, v191
	v_add_f32_e32 v110, v104, v106
	v_mov_b32_e32 v104, v108
	s_nop 1
	v_permlane16_swap_b32_e32 v108, v104
	v_add_f32_e32 v104, v108, v104
	v_mov_b32_e32 v106, v104
	s_nop 1
	v_permlane32_swap_b32_e32 v104, v106
	v_add_f32_e32 v108, v104, v106
	v_mov_b32_e32 v104, v196
	s_nop 1
	v_permlane16_swap_b32_e32 v196, v104
	v_add_f32_e32 v104, v196, v104
	v_mov_b32_e32 v106, v104
	s_nop 1
	v_permlane32_swap_b32_e32 v104, v106
	v_add_f32_e32 v106, v104, v106
	v_mov_b32_e32 v104, v190
	s_nop 1
	v_permlane16_swap_b32_e32 v190, v104
	v_add_f32_e32 v104, v190, v104
	v_mov_b32_e32 v190, v104
	s_nop 1
	v_permlane32_swap_b32_e32 v104, v190
	v_add_f32_e32 v104, v104, v190
	v_add_u32_e32 v190, 0x2400, v178
	ds_read2_b32 v[238:239], v190 offset0:64 offset1:80
	ds_read2_b32 v[240:241], v190 offset0:96 offset1:112
	ds_read_b128 v[190:193], v177 offset:8448
	ds_read_b128 v[194:197], v177 offset:8464
	ds_read_b128 v[198:201], v177 offset:8480
	ds_read_b128 v[202:205], v177 offset:8496
	ds_read_b128 v[206:209], v177 offset:8704
	ds_read_b128 v[210:213], v177 offset:8720
	ds_read_b128 v[214:217], v177 offset:8736
	ds_read_b128 v[218:221], v177 offset:8752
	ds_read_b128 v[222:225], v177 offset:8960
	ds_read_b128 v[226:229], v177 offset:8976
	ds_read_b128 v[230:233], v177 offset:8992
	ds_read_b128 v[234:237], v177 offset:9008
	s_waitcnt lgkmcnt(3)
; #define LAS __attribute__((address_space(3)))
; template <int MODE>
; __device__ __forceinline__ void scan_item(const DArgs& a, LAS float* W  , int row0, int nsteps, int h, int lane, bool first_is_start, const float* shift_prev  ,
;                                           const float* S_init  , float* S_final  , float* Uout, float* Pout) {
;     ...
;         for (int hf = 0; hf < NS; ++hf) {
;             f32x2 wv[PW], bv[PW], kv[PW];
; #pragma unroll
;             for (int m = 0; m < PW / 2; ++m) { const int o_ = 16 * ib + 2 * PW * hf + 4 * m; const f32x4 t0 = *(const LAS f32x4*)(W + 64 + o_), t1 = *(const LAS f32x4*)(W + 128 + o_), t2 = MODE == 2 ? t1 : *(const LAS f32x4*)(W + 192 + o_);
;                 wv[2 * m] = (f32x2){t0.x, t0.y}; wv[2 * m + 1] = (f32x2){t0.z, t0.w}; bv[2 * m] = (f32x2){t1.x, t1.y}; bv[2 * m + 1] = (f32x2){t1.z, t1.w}; kv[2 * m] = (f32x2){t2.x, t2.y}; kv[2 * m + 1] = (f32x2){t2.z, t2.w}; }
; #pragma unroll
;             for (int q = 0; q < 4; ++q) {
;                 const f32x2 sa2 = (f32x2){sa[q], sa[q]}, v2 = (f32x2){vq[q], vq[q]};
; #pragma unroll
;                 for (int p = 0; p < PW; ++p) { if constexpr (MODE == 2) S[q][PW * hf + p] = S[q][PW * hf + p] * wv[p] + sa2 * bv[p]; else S[q][PW * hf + p] = S[q][PW * hf + p] * wv[p] + (sa2 * bv[p] + v2 * kv[p]); }
;             }
;         }
;     ...
;         pv = pn; raw1 = raw2;
	v_pk_mul_f32 v[242:243], v[238:239], v[222:223] op_sel_hi:[0,1]
	v_pk_fma_f32 v[242:243], v[110:111], v[206:207], v[242:243] op_sel_hi:[0,1,1]
	v_pk_fma_f32 v[68:69], v[68:69], v[190:191], v[242:243]
	v_pk_mul_f32 v[242:243], v[238:239], v[224:225] op_sel_hi:[0,1]
	v_pk_fma_f32 v[242:243], v[110:111], v[208:209], v[242:243] op_sel_hi:[0,1,1]
	v_pk_fma_f32 v[70:71], v[70:71], v[192:193], v[242:243]
	s_waitcnt lgkmcnt(2)
	v_pk_mul_f32 v[242:243], v[238:239], v[226:227] op_sel_hi:[0,1]
	v_pk_fma_f32 v[242:243], v[110:111], v[210:211], v[242:243] op_sel_hi:[0,1,1]
	v_pk_fma_f32 v[64:65], v[64:65], v[194:195], v[242:243]
	v_pk_mul_f32 v[242:243], v[238:239], v[228:229] op_sel_hi:[0,1]
	v_pk_fma_f32 v[242:243], v[110:111], v[212:213], v[242:243] op_sel_hi:[0,1,1]
	v_pk_fma_f32 v[66:67], v[66:67], v[196:197], v[242:243]
	v_mov_b32_e32 v242, v239
	v_pk_mul_f32 v[244:245], v[242:243], v[222:223] op_sel_hi:[0,1]
	v_pk_fma_f32 v[244:245], v[108:109], v[206:207], v[244:245] op_sel_hi:[0,1,1]
	v_pk_fma_f32 v[52:53], v[52:53], v[190:191], v[244:245]
	v_pk_mul_f32 v[244:245], v[242:243], v[224:225] op_sel_hi:[0,1]
	v_pk_fma_f32 v[244:245], v[108:109], v[208:209], v[244:245] op_sel_hi:[0,1,1]
	v_pk_fma_f32 v[54:55], v[54:55], v[192:193], v[244:245]
	v_pk_mul_f32 v[244:245], v[242:243], v[226:227] op_sel_hi:[0,1]
	v_pk_fma_f32 v[244:245], v[108:109], v[210:211], v[244:245] op_sel_hi:[0,1,1]
	v_pk_fma_f32 v[48:49], v[48:49], v[194:195], v[244:245]
	v_pk_mul_f32 v[244:245], v[242:243], v[228:229] op_sel_hi:[0,1]
	v_pk_fma_f32 v[244:245], v[108:109], v[212:213], v[244:245] op_sel_hi:[0,1,1]
	v_pk_fma_f32 v[50:51], v[50:51], v[196:197], v[244:245]
	v_pk_mul_f32 v[244:245], v[240:241], v[222:223] op_sel_hi:[0,1]
	v_pk_fma_f32 v[244:245], v[106:107], v[206:207], v[244:245] op_sel_hi:[0,1,1]
	v_pk_fma_f32 v[28:29], v[28:29], v[190:191], v[244:245]
	v_pk_mul_f32 v[244:245], v[240:241], v[224:225] op_sel_hi:[0,1]
	v_pk_fma_f32 v[244:245], v[106:107], v[208:209], v[244:245] op_sel_hi:[0,1,1]
	v_pk_fma_f32 v[30:31], v[30:31], v[192:193], v[244:245]
	v_pk_mul_f32 v[244:245], v[240:241], v[226:227] op_sel_hi:[0,1]
	v_pk_fma_f32 v[244:245], v[106:107], v[210:211], v[244:245] op_sel_hi:[0,1,1]
	v_pk_fma_f32 v[24:25], v[24:25], v[194:195], v[244:245]
	v_pk_mul_f32 v[244:245], v[240:241], v[228:229] op_sel_hi:[0,1]
	v_pk_fma_f32 v[244:245], v[106:107], v[212:213], v[244:245] op_sel_hi:[0,1,1]
	v_pk_fma_f32 v[26:27], v[26:27], v[196:197], v[244:245]
	v_mov_b32_e32 v244, v241
	v_pk_mul_f32 v[222:223], v[244:245], v[222:223] op_sel_hi:[0,1]
	v_pk_fma_f32 v[206:207], v[104:105], v[206:207], v[222:223] op_sel_hi:[0,1,1]
	v_pk_fma_f32 v[12:13], v[12:13], v[190:191], v[206:207]
	v_pk_mul_f32 v[190:191], v[244:245], v[224:225] op_sel_hi:[0,1]
	v_pk_fma_f32 v[190:191], v[104:105], v[208:209], v[190:191] op_sel_hi:[0,1,1]
	v_pk_fma_f32 v[14:15], v[14:15], v[192:193], v[190:191]
	v_pk_mul_f32 v[190:191], v[244:245], v[226:227] op_sel_hi:[0,1]
	v_pk_fma_f32 v[190:191], v[104:105], v[210:211], v[190:191] op_sel_hi:[0,1,1]
	v_pk_fma_f32 v[8:9], v[8:9], v[194:195], v[190:191]
	v_pk_mul_f32 v[190:191], v[244:245], v[228:229] op_sel_hi:[0,1]
	v_pk_fma_f32 v[190:191], v[104:105], v[212:213], v[190:191] op_sel_hi:[0,1,1]
	v_pk_fma_f32 v[10:11], v[10:11], v[196:197], v[190:191]
	s_waitcnt lgkmcnt(1)
	v_pk_mul_f32 v[190:191], v[238:239], v[230:231] op_sel_hi:[0,1]
	v_pk_fma_f32 v[190:191], v[110:111], v[214:215], v[190:191] op_sel_hi:[0,1,1]
	v_pk_fma_f32 v[60:61], v[60:61], v[198:199], v[190:191]
	v_pk_mul_f32 v[190:191], v[238:239], v[232:233] op_sel_hi:[0,1]
	v_pk_fma_f32 v[190:191], v[110:111], v[216:217], v[190:191] op_sel_hi:[0,1,1]
	v_pk_fma_f32 v[62:63], v[62:63], v[200:201], v[190:191]
	s_waitcnt lgkmcnt(0)
	v_pk_mul_f32 v[190:191], v[238:239], v[234:235] op_sel_hi:[0,1]
	v_pk_fma_f32 v[190:191], v[110:111], v[218:219], v[190:191] op_sel_hi:[0,1,1]
	v_pk_fma_f32 v[56:57], v[56:57], v[202:203], v[190:191]
	v_pk_mul_f32 v[190:191], v[238:239], v[236:237] op_sel_hi:[0,1]
	v_pk_fma_f32 v[190:191], v[110:111], v[220:221], v[190:191] op_sel_hi:[0,1,1]
	v_pk_fma_f32 v[58:59], v[58:59], v[204:205], v[190:191]
	v_pk_mul_f32 v[190:191], v[242:243], v[230:231] op_sel_hi:[0,1]
	v_pk_fma_f32 v[190:191], v[108:109], v[214:215], v[190:191] op_sel_hi:[0,1,1]
	v_pk_fma_f32 v[44:45], v[44:45], v[198:199], v[190:191]
	v_pk_mul_f32 v[190:191], v[242:243], v[232:233] op_sel_hi:[0,1]
	v_pk_fma_f32 v[190:191], v[108:109], v[216:217], v[190:191] op_sel_hi:[0,1,1]
	v_pk_fma_f32 v[46:47], v[46:47], v[200:201], v[190:191]
	v_pk_mul_f32 v[190:191], v[242:243], v[234:235] op_sel_hi:[0,1]
	v_pk_fma_f32 v[190:191], v[108:109], v[218:219], v[190:191] op_sel_hi:[0,1,1]
	v_pk_fma_f32 v[40:41], v[40:41], v[202:203], v[190:191]
	v_pk_mul_f32 v[190:191], v[242:243], v[236:237] op_sel_hi:[0,1]
	v_pk_fma_f32 v[190:191], v[108:109], v[220:221], v[190:191] op_sel_hi:[0,1,1]
	v_pk_fma_f32 v[42:43], v[42:43], v[204:205], v[190:191]
	v_pk_mul_f32 v[190:191], v[240:241], v[230:231] op_sel_hi:[0,1]
	v_pk_fma_f32 v[190:191], v[106:107], v[214:215], v[190:191] op_sel_hi:[0,1,1]
	v_pk_fma_f32 v[20:21], v[20:21], v[198:199], v[190:191]
	v_pk_mul_f32 v[190:191], v[240:241], v[232:233] op_sel_hi:[0,1]
	v_pk_fma_f32 v[190:191], v[106:107], v[216:217], v[190:191] op_sel_hi:[0,1,1]
	v_pk_fma_f32 v[22:23], v[22:23], v[200:201], v[190:191]
	v_pk_mul_f32 v[190:191], v[240:241], v[234:235] op_sel_hi:[0,1]
	v_pk_fma_f32 v[190:191], v[106:107], v[218:219], v[190:191] op_sel_hi:[0,1,1]
	v_pk_fma_f32 v[16:17], v[16:17], v[202:203], v[190:191]
	v_pk_mul_f32 v[190:191], v[240:241], v[236:237] op_sel_hi:[0,1]
	v_pk_fma_f32 v[190:191], v[106:107], v[220:221], v[190:191] op_sel_hi:[0,1,1]
	v_pk_fma_f32 v[18:19], v[18:19], v[204:205], v[190:191]
	v_pk_mul_f32 v[190:191], v[244:245], v[230:231] op_sel_hi:[0,1]
	v_pk_fma_f32 v[190:191], v[104:105], v[214:215], v[190:191] op_sel_hi:[0,1,1]
	v_pk_fma_f32 v[36:37], v[36:37], v[198:199], v[190:191]
	v_pk_mul_f32 v[190:191], v[244:245], v[232:233] op_sel_hi:[0,1]
	v_pk_fma_f32 v[190:191], v[104:105], v[216:217], v[190:191] op_sel_hi:[0,1,1]
	v_pk_fma_f32 v[38:39], v[38:39], v[200:201], v[190:191]
	v_pk_mul_f32 v[190:191], v[244:245], v[234:235] op_sel_hi:[0,1]
	v_pk_fma_f32 v[190:191], v[104:105], v[218:219], v[190:191] op_sel_hi:[0,1,1]
	v_pk_fma_f32 v[32:33], v[32:33], v[202:203], v[190:191]
	v_pk_mul_f32 v[190:191], v[244:245], v[236:237] op_sel_hi:[0,1]
	v_pk_fma_f32 v[190:191], v[104:105], v[220:221], v[190:191] op_sel_hi:[0,1,1]
	v_pk_fma_f32 v[34:35], v[34:35], v[204:205], v[190:191]
	s_waitcnt vmcnt(2)
	v_perm_b32 v104, v188, v189, s26
	s_waitcnt vmcnt(0)
	v_mov_b32_e32 v106, v187
	v_mov_b32_e32 v108, v186
	s_cbranch_scc1 .LBB0_574
;     __device__ __forceinline__ const float* in(int i) const { return (const float*)(const __attribute__((address_space(1))) float*)ld(i); }
;     __device__ __forceinline__ unsigned char* wsp() const { return (unsigned char*)(__attribute__((address_space(1))) unsigned char*)ld(33); }
; __device__ __forceinline__ float bf2f(bf16_t b) { return __uint_as_float(((unsigned)b) << 16); }
; template <int MODE>
; __device__ __forceinline__ void scan_item(const DArgs& a, LAS float* W  , int row0, int nsteps, int h, int lane, bool first_is_start, const float* shift_prev  ,
;                                           const float* S_init  , float* S_final  , float* Uout, float* Pout) {
;     const bf16_t* P = (const bf16_t*)(a.wsp() + W_P); const float* L = (const float*)(a.wsp() + W_L); bf16_t* mix = (bf16_t*)(a.wsp() + W_MIX);
;     const int c = h * 64 + lane, ib = lane >> 4, il = lane & 15;
;     ScanConst k; k.mu_r = a.in(I_MU)[c]; k.mu_k = a.in(I_MU)[1024 + c]; k.mu_v = a.in(I_MU)[2048 + c]; k.w0 = a.in(I_W0)[c]; k.a0 = a.in(I_A0)[c];
;     k.kkc = a.in(I_KK)[c]; k.kac = a.in(I_KA)[c]; k.rk = a.in(I_RK)[c]; k.lnw = a.in(I_LNW)[c]; k.lnb = a.in(I_LNB)[c];
;     float zr_p, zk_p, zv_p;
;     if (!first_is_start) { const bf16_t* p = P + (size_t)(row0 - 1) * DIN0 + DPOOL + c; zr_p = bf2f(p[0]); zk_p = bf2f(p[1024]); zv_p = bf2f(p[2048]); }
;     else if (shift_prev) { zr_p = shift_prev[c]; zk_p = shift_prev[1024 + c]; zv_p = shift_prev[2048 + c]; }
;     else { zr_p = 0.f; zk_p = 0.f; zv_p = 0.f; }
;     ...
;         float* dst = MODE == 0 ? Uout : Pout;
; #pragma unroll
;         for (int q = 0; q < 4; ++q)
; #pragma unroll
;             for (int m = 0; m < 4; ++m) *(f32x4*)(dst + (il + 16 * q) * 64 + 16 * ib + 4 * m) = (f32x4){S[q][2 * m].x, S[q][2 * m].y, S[q][2 * m + 1].x, S[q][2 * m + 1].y};
	v_ashrrev_i32_e32 v81, 31, v80
	v_lshlrev_b64 v[94:95], 14, v[80:81]
	v_lshl_add_u64 v[94:95], s[14:15], 0, v[94:95]
	v_mov_b32_e32 v91, v83
	v_lshl_add_u64 v[94:95], v[94:95], 0, v[90:91]
	v_mov_b32_e32 v89, v83
	v_lshl_add_u64 v[94:95], v[94:95], 0, v[88:89]
	v_add_co_u32_e32 v98, vcc, 0x12b58000, v94
	v_lshl_add_u64 v[96:97], v[94:95], 0, s[8:9]
	s_nop 0
	v_addc_co_u32_e32 v99, vcc, 0, v95, vcc
	global_store_dwordx4 v[98:99], v[68:71], off
	global_store_dwordx4 v[96:97], v[64:67], off offset:16
	global_store_dwordx4 v[96:97], v[60:63], off offset:32
	global_store_dwordx4 v[96:97], v[56:59], off offset:48
	v_readfirstlane_b32 s1, v1
	v_readfirstlane_b32 s0, v0
	v_add_co_u32_e32 v56, vcc, s27, v94
	v_readfirstlane_b32 s15, v87
	s_nop 0
	v_addc_co_u32_e32 v57, vcc, 0, v95, vcc
	v_add_co_u32_e32 v58, vcc, s28, v94
	v_readfirstlane_b32 s14, v86
	s_nop 0
	v_addc_co_u32_e32 v59, vcc, 0, v95, vcc
	global_store_dwordx4 v[58:59], v[52:55], off offset:-4096
	global_store_dwordx4 v[56:57], v[48:51], off offset:16
	global_store_dwordx4 v[56:57], v[44:47], off offset:32
	global_store_dwordx4 v[56:57], v[40:43], off offset:48
	global_store_dwordx4 v[58:59], v[28:31], off
	global_store_dwordx4 v[58:59], v[24:27], off offset:16
	global_store_dwordx4 v[58:59], v[20:23], off offset:32
	global_store_dwordx4 v[58:59], v[16:19], off offset:48
	v_readfirstlane_b32 s17, v5
	v_readfirstlane_b32 s16, v4
	v_add_co_u32_e32 v16, vcc, s29, v94
	v_mov_b32_e32 v40, 0
	s_nop 0
	v_addc_co_u32_e32 v17, vcc, 0, v95, vcc
	global_store_dwordx4 v[16:17], v[12:15], off
	global_store_dwordx4 v[16:17], v[8:11], off offset:16
	global_store_dwordx4 v[16:17], v[36:39], off offset:32
	global_store_dwordx4 v[16:17], v[32:35], off offset:48
	v_lshl_add_u64 v[8:9], s[0:1], 0, v[82:83]
	v_add_co_u32_e32 v8, vcc, s22, v8
	v_readfirstlane_b32 s1, v3
	s_nop 0
	v_addc_co_u32_e32 v9, vcc, 0, v9, vcc
	v_readfirstlane_b32 s0, v2
	global_load_dword v89, v[8:9], off
	s_nop 3
	global_load_dword v91, v82, s[0:1]
	global_load_dword v98, v82, s[14:15]
	global_load_dword v99, v82, s[16:17]
	v_readfirstlane_b32 s14, v84
	v_readfirstlane_b32 s15, v85
	s_add_u32 s16, s14, 0x14c58000
	s_addc_u32 s17, s15, 0
	s_and_saveexec_b64 s[0:1], s[4:5]
	s_cbranch_execz .LBB0_577
	v_mov_b64_e32 v[8:9], s[16:17]
	v_mad_i64_i32 v[8:9], s[4:5], v180, s24, v[8:9]
	v_mov_b32_e32 v73, v83
	v_lshl_add_u64 v[8:9], v[8:9], 0, v[72:73]
	v_add_co_u32_e32 v8, vcc, 0x1000, v8
	s_nop 1
	v_addc_co_u32_e32 v9, vcc, 0, v9, vcc
	global_load_ushort v8, v[8:9], off
	s_waitcnt vmcnt(0)
	v_lshlrev_b32_e32 v40, 16, v8
